# PA epilogue of dk/dv tiles (pn 2..5) delayed by 2 x s_sleep 127 to de-phase their store burst
# speedup vs baseline: 1.0060x; 1.0060x over previous
.LBB0_392:
	s_cmp_lt_u32 s72, 2
	s_cbranch_scc1 .Lpd_skip
	s_cmp_gt_u32 s72, 5
	s_cbranch_scc1 .Lpd_skip
	s_sleep 127
	s_sleep 127
